# symmetric pipelined diff loop; waves 0-3 compute the next tile's ALiBi bias init behind their MFMA core, waves 4-7 in front of it (half-staggered VALU)
# speedup vs baseline: 1.0245x; 1.0023x over previous
; __device__ __forceinline__ int opaque_tid(int wv) { int lane_; asm volatile("v_mbcnt_lo_u32_b32 %0, -1, 0\n\tv_mbcnt_hi_u32_b32 %0, -1, %0" : "=v"(lane_)); return wv * 64 + lane_; }
; __device__ __forceinline__ int v_rd_base(int lane) { return ((lane & 3) << 3) | (((lane >> 2) & 3) << 6) | (((lane >> 4) & 1) << 5) | (((lane >> 5) & 1) << 8); }
; #define ENDI() do { asm volatile("s_waitcnt vmcnt(0)" ::: "memory"); __syncthreads(); } while (0)
; #define BIAS(P0, P1, t) bias_init(P0, P1, (float)(iposk - (t) * KVBLK), nslope2, nM2, relw + (t) * KVBLK)
; __device__ __forceinline__ void diff_unit(const DiffArgs& A, int b, int h, int qb, char* lds, int wv) {
;     ...
;     float l_reg = 0; f32x16 o[4] = {}; bf16x8 qr[4];
;     { const char* Qw = Pb + (size_t)(qb * 128 + wq * 32) * (INC * 2) + (C_DQ + c * 64) * 2; const unsigned qoff = (unsigned)((r32 * INC + hi * 8) * 2);
; #pragma unroll
;       for (int d0 = 0; d0 < 4; ++d0) qr[d0] = *reinterpret_cast<const bf16x8*>(Qw + qoff + d0 * 32); }
;     const int colB0 = c * 128;
;     const int krow = wid * 4 + (lane >> 4), kcc = (lane & 15) ^ (krow & 15);
;     const unsigned koff = (unsigned)((krow * INC + kcc * 8) * 2);
;     const int vkey = (wid >> 2) * 16 + (((wid >> 1) & 1) << 3) + (((lane >> 4) & 1) << 2) + ((lane >> 2) & 3)  , vcol = ((wid & 1) * 2 + (lane >> 5)) * 32 + (lane & 3) * 8;
;     const unsigned voff = (unsigned)((vkey * INC + vcol) * 2 + (C_DV - C_DK) * 2);
;     const int vb0 = (int)(uintptr_t)V_lds + v_rd_base(lane);
;     const char* Pk = Pb + (size_t)(t_lo * KVBLK) * (INC * 2) + C_DK * 2; int iposk = ipos - t_lo * KVBLK - 4 * hi; asm volatile("" : "+v"(iposk));     const int relw = t_lo * KVBLK - (qb * 128 + wq * 32);
;     typedef __attribute__((address_space(3))) unsigned lds_u32;
;     __attribute__((address_space(3))) unsigned char* ldsA = (__attribute__((address_space(3))) unsigned char*)lds + wid * 1024;
;     ...
;     f32x16 pA0, pA1, pB0, pB1; bf16x8 pa0, pa1, pa2, pa3; const int NT = nt;
;     STAGE(0); ENDI();
;     STAGE(1);
;     BIAS(pA0, pA1, 0); qkt<4>(pA0, pA1, K_lds, qr, r32, hi, colB0);
;     ...
;     if (c == 0) {
;     ...
;         const int lp_ = opaque_tid(wv) & 63, r32p = lp_ & 31, hip = lp_ >> 5;
;         exp_half(pA0);
;         ENDI();
; #pragma unroll 1
;         for (int j = 1; j + 1 < NT; j += 2) {
.Lsym_entry:
	v_mov_b32_e32 v0, 0
	v_mov_b32_e32 v1, 0
	v_mov_b32_e32 v2, 0
	v_mov_b32_e32 v3, 0
	v_mov_b32_e32 v4, 0
	v_mov_b32_e32 v5, 0
	v_mov_b32_e32 v6, 0
	v_mov_b32_e32 v7, 0
	v_mov_b32_e32 v8, 0
	v_mov_b32_e32 v9, 0
	v_mov_b32_e32 v10, 0
	v_mov_b32_e32 v11, 0
	v_mov_b32_e32 v12, 0
	v_mov_b32_e32 v13, 0
	v_mov_b32_e32 v14, 0
	v_mov_b32_e32 v15, 0
	v_mov_b32_e32 v16, 0
	v_mov_b32_e32 v17, 0
	v_mov_b32_e32 v18, 0
	v_mov_b32_e32 v19, 0
	v_mov_b32_e32 v20, 0
	v_mov_b32_e32 v21, 0
	v_mov_b32_e32 v22, 0
	v_mov_b32_e32 v23, 0
	v_mov_b32_e32 v24, 0
	v_mov_b32_e32 v25, 0
	v_mov_b32_e32 v26, 0
	v_mov_b32_e32 v27, 0
	v_mov_b32_e32 v28, 0
	v_mov_b32_e32 v29, 0
	v_mov_b32_e32 v30, 0
	v_mov_b32_e32 v31, 0
	v_mov_b32_e32 v32, 0
	v_mov_b32_e32 v33, 0
	v_mov_b32_e32 v34, 0
	v_mov_b32_e32 v35, 0
	v_mov_b32_e32 v36, 0
	v_mov_b32_e32 v37, 0
	v_mov_b32_e32 v38, 0
	v_mov_b32_e32 v39, 0
	v_mov_b32_e32 v40, 0
	v_mov_b32_e32 v41, 0
	v_mov_b32_e32 v42, 0
	v_mov_b32_e32 v43, 0
	v_mov_b32_e32 v44, 0
	v_mov_b32_e32 v45, 0
	v_mov_b32_e32 v46, 0
	v_mov_b32_e32 v47, 0
	v_mov_b32_e32 v48, 0
	v_mov_b32_e32 v49, 0
	v_mov_b32_e32 v50, 0
	v_mov_b32_e32 v51, 0
	v_mov_b32_e32 v52, 0
	v_mov_b32_e32 v53, 0
	v_mov_b32_e32 v54, 0
	v_mov_b32_e32 v55, 0
	v_mov_b32_e32 v56, 0
	v_mov_b32_e32 v57, 0
	v_mov_b32_e32 v58, 0
	v_mov_b32_e32 v59, 0
	v_mov_b32_e32 v60, 0
	v_mov_b32_e32 v61, 0
	v_mov_b32_e32 v62, 0
	v_mov_b32_e32 v63, 0
	v_mov_b32_e32 v182, 0
	v_mbcnt_lo_u32_b32 v190, -1, 0
	v_mbcnt_hi_u32_b32 v190, -1, v190
	v_and_b32_e32 v191, 31, v190
	v_lshrrev_b32_e32 v187, 5, v190
	v_lshlrev_b32_e32 v185, 4, v187
	v_or_b32_e32 v185, s52, v185
	v_and_b32_e32 v183, 15, v191
	v_lshlrev_b32_e32 v183, 4, v183
	v_xor_b32_e32 v185, v185, v183
	v_lshlrev_b32_e32 v183, 8, v191
	v_xor_b32_e32 v178, 0, v185
	v_add_u32_e32 v178, v178, v183
	v_xor_b32_e32 v179, 32, v185
	v_add_u32_e32 v179, v179, v183
	v_xor_b32_e32 v180, 64, v185
	v_add_u32_e32 v180, v180, v183
	v_xor_b32_e32 v181, 96, v185
	v_add_u32_e32 v181, v181, v183
	s_mov_b32 s54, 0
	s_mov_b32 s55, 0
	s_mov_b32 s58, 0x8000
	s_add_u32 s56, s20, 0x1c1e00
	s_addc_u32 s57, s21, 0
	v_exp_f32_e32 v80, v80
	v_exp_f32_e32 v81, v81
	v_exp_f32_e32 v82, v82
	v_exp_f32_e32 v83, v83
	v_add_f32_e32 v182, v80, v182
	v_add_f32_e32 v182, v81, v182
	v_cvt_pk_bf16_f32 v128, v80, v81
	v_exp_f32_e32 v84, v84
	v_exp_f32_e32 v85, v85
	v_add_f32_e32 v182, v82, v182
	v_add_f32_e32 v182, v83, v182
	v_cvt_pk_bf16_f32 v129, v82, v83
	v_exp_f32_e32 v86, v86
	v_exp_f32_e32 v87, v87
	v_add_f32_e32 v182, v84, v182
	v_add_f32_e32 v182, v85, v182
	v_cvt_pk_bf16_f32 v130, v84, v85
	v_add_f32_e32 v182, v86, v182
	v_add_f32_e32 v182, v87, v182
	v_cvt_pk_bf16_f32 v131, v86, v87
	s_cmpk_gt_u32 s3, 0xff
	s_cbranch_scc0 .Lsym_entryB

; __device__ __forceinline__ int opaque_tid(int wv) { int lane_; asm volatile("v_mbcnt_lo_u32_b32 %0, -1, 0\n\tv_mbcnt_hi_u32_b32 %0, -1, %0" : "=v"(lane_)); return wv * 64 + lane_; }
; #define SBAR() __builtin_amdgcn_sched_barrier(0)
; #define BIAS(P0, P1, t) bias_init(P0, P1, (float)(iposk - (t) * KVBLK), nslope2, nM2, relw + (t) * KVBLK)
; template <int KS> __device__ __forceinline__ void pv_ks(f32x16* o, int vb, bf16x8 pa) {
;     const s16x4 l0 = tr_read<v_rd_off(0, KS, 0)>(vb), h0 = tr_read<v_rd_off(0, KS, 1)>(vb), l1 = tr_read<v_rd_off(1, KS, 0)>(vb), h1 = tr_read<v_rd_off(1, KS, 1)>(vb);
;     const s16x4 l2 = tr_read<v_rd_off(2, KS, 0)>(vb), h2 = tr_read<v_rd_off(2, KS, 1)>(vb), l3 = tr_read<v_rd_off(3, KS, 0)>(vb), h3 = tr_read<v_rd_off(3, KS, 1)>(vb);
;     ...
;     asm volatile("s_waitcnt lgkmcnt(6)" ::: "memory"); SBAR();
;     o[0] = __builtin_amdgcn_mfma_f32_32x32x16_bf16(pa, PK(l0, h0), o[0], 0, 0, 0);
;     asm volatile("s_waitcnt lgkmcnt(4)" ::: "memory"); SBAR();
;     o[1] = __builtin_amdgcn_mfma_f32_32x32x16_bf16(pa, PK(l1, h1), o[1], 0, 0, 0);
;     asm volatile("s_waitcnt lgkmcnt(2)" ::: "memory"); SBAR();
;     o[2] = __builtin_amdgcn_mfma_f32_32x32x16_bf16(pa, PK(l2, h2), o[2], 0, 0, 0);
;     asm volatile("s_waitcnt lgkmcnt(0)" ::: "memory"); SBAR();
;     o[3] = __builtin_amdgcn_mfma_f32_32x32x16_bf16(pa, PK(l3, h3), o[3], 0, 0, 0);
;     ...
; }
; __device__ __forceinline__ void pv_d0(f32x16* o, int vb, bf16x8 pa0, bf16x8 pa1, bf16x8 pa2, bf16x8 pa3) {
;     __builtin_amdgcn_s_setprio(1);
;     pv_ks<0>(o, vb, pa0); pv_ks<1>(o, vb, pa1); pv_ks<2>(o, vb, pa2); pv_ks<3>(o, vb, pa3);
;     __builtin_amdgcn_s_setprio(0);
; }
; __device__ __forceinline__ void diff_unit(const DiffArgs& A, int b, int h, int qb, char* lds, int wv) {
;     ...
;         { const int lt_ = opaque_tid(wv) & 63;
;           SBAR(); BIAS(pB0, pB1, NT - 1); qkt<4>(pB0, pB1, K_lds + SLOT(NT - 1), qr, lt_ & 31, lt_ >> 5, colB0); }
;         exp_half(pA1); pack_p(pA0, pA1, l_reg, pa0, pa1, pa2, pa3); SBAR();
;         pv_d0(o, vb0 + SLOT(NT - 2), pa0, pa1, pa2, pa3); exp_half(pB0);
;         exp_half(pB1); pack_p(pB0, pB1, l_reg, pa0, pa1, pa2, pa3); SBAR();
;         pv_d0(o, vb0 + SLOT(NT - 1), pa0, pa1, pa2, pa3);
.Lsym_last:
	s_waitcnt vmcnt(0)
	s_barrier
	v_add_u32_e32 v184, s55, v252
	ds_read_b64_tr_b16 v[144:145], v184 offset:0
	ds_read_b64_tr_b16 v[146:147], v184 offset:2048
	ds_read_b64_tr_b16 v[148:149], v184 offset:512
	ds_read_b64_tr_b16 v[150:151], v184 offset:2560
	ds_read_b64_tr_b16 v[152:153], v184 offset:1024
	ds_read_b64_tr_b16 v[154:155], v184 offset:3072
	ds_read_b64_tr_b16 v[156:157], v184 offset:1536
	ds_read_b64_tr_b16 v[158:159], v184 offset:3584
	s_waitcnt lgkmcnt(6)
	v_mfma_f32_32x32x16_bf16 v[48:63], v[128:131], v[144:147], v[48:63]
	ds_read_b64_tr_b16 v[144:145], v184 offset:4096
	ds_read_b64_tr_b16 v[146:147], v184 offset:6144
	v_exp_f32_e32 v120, v120
	v_exp_f32_e32 v121, v121
	s_waitcnt lgkmcnt(6)
	v_mfma_f32_32x32x16_bf16 v[32:47], v[128:131], v[148:151], v[32:47]
	ds_read_b64_tr_b16 v[148:149], v184 offset:4608
	ds_read_b64_tr_b16 v[150:151], v184 offset:6656
	v_exp_f32_e32 v122, v122
	v_exp_f32_e32 v123, v123
	v_add_f32_e32 v182, v120, v182
	v_add_f32_e32 v182, v121, v182
	v_cvt_pk_bf16_f32 v132, v120, v121
	s_waitcnt lgkmcnt(6)
	v_mfma_f32_32x32x16_bf16 v[16:31], v[128:131], v[152:155], v[16:31]
	ds_read_b64_tr_b16 v[152:153], v184 offset:5120
	ds_read_b64_tr_b16 v[154:155], v184 offset:7168
	v_exp_f32_e32 v124, v124
	v_exp_f32_e32 v125, v125
	v_add_f32_e32 v182, v122, v182
	v_add_f32_e32 v182, v123, v182
	v_cvt_pk_bf16_f32 v133, v122, v123
	s_waitcnt lgkmcnt(6)
	v_mfma_f32_32x32x16_bf16 v[0:15], v[128:131], v[156:159], v[0:15]
	ds_read_b64_tr_b16 v[156:157], v184 offset:5632
	ds_read_b64_tr_b16 v[158:159], v184 offset:7680
	v_exp_f32_e32 v126, v126
	v_exp_f32_e32 v127, v127
	v_add_f32_e32 v182, v124, v182
	v_add_f32_e32 v182, v125, v182
	v_cvt_pk_bf16_f32 v134, v124, v125
	v_add_f32_e32 v182, v126, v182
	v_add_f32_e32 v182, v127, v182
	v_cvt_pk_bf16_f32 v135, v126, v127
	s_nop 1
	s_waitcnt lgkmcnt(6)
	v_mfma_f32_32x32x16_bf16 v[48:63], v[132:135], v[144:147], v[48:63]
	ds_read_b64_tr_b16 v[144:145], v184 offset:8192
	ds_read_b64_tr_b16 v[146:147], v184 offset:10240
	v_exp_f32_e32 v96, v96
	v_exp_f32_e32 v97, v97
	s_waitcnt lgkmcnt(6)
	v_mfma_f32_32x32x16_bf16 v[32:47], v[132:135], v[148:151], v[32:47]
	ds_read_b64_tr_b16 v[148:149], v184 offset:8704
	ds_read_b64_tr_b16 v[150:151], v184 offset:10752
	v_exp_f32_e32 v98, v98
	v_exp_f32_e32 v99, v99
	v_add_f32_e32 v182, v96, v182
	v_add_f32_e32 v182, v97, v182
	v_cvt_pk_bf16_f32 v136, v96, v97
	s_waitcnt lgkmcnt(6)
	v_mfma_f32_32x32x16_bf16 v[16:31], v[132:135], v[152:155], v[16:31]
	ds_read_b64_tr_b16 v[152:153], v184 offset:9216
	ds_read_b64_tr_b16 v[154:155], v184 offset:11264
	v_exp_f32_e32 v100, v100
	v_exp_f32_e32 v101, v101
	v_add_f32_e32 v182, v98, v182
	v_add_f32_e32 v182, v99, v182
	v_cvt_pk_bf16_f32 v137, v98, v99
	s_waitcnt lgkmcnt(6)
	v_mfma_f32_32x32x16_bf16 v[0:15], v[132:135], v[156:159], v[0:15]
	ds_read_b64_tr_b16 v[156:157], v184 offset:9728
	ds_read_b64_tr_b16 v[158:159], v184 offset:11776
	v_exp_f32_e32 v102, v102
	v_exp_f32_e32 v103, v103
	v_add_f32_e32 v182, v100, v182
	v_add_f32_e32 v182, v101, v182
	v_cvt_pk_bf16_f32 v138, v100, v101
	v_add_f32_e32 v182, v102, v182
	v_add_f32_e32 v182, v103, v182
	v_cvt_pk_bf16_f32 v139, v102, v103
	s_nop 1
	s_waitcnt lgkmcnt(6)
	v_mfma_f32_32x32x16_bf16 v[48:63], v[136:139], v[144:147], v[48:63]
	ds_read_b64_tr_b16 v[144:145], v184 offset:12288
	ds_read_b64_tr_b16 v[146:147], v184 offset:14336
	v_exp_f32_e32 v104, v104
	v_exp_f32_e32 v105, v105
	s_waitcnt lgkmcnt(6)
	v_mfma_f32_32x32x16_bf16 v[32:47], v[136:139], v[148:151], v[32:47]
	ds_read_b64_tr_b16 v[148:149], v184 offset:12800
	ds_read_b64_tr_b16 v[150:151], v184 offset:14848
	v_exp_f32_e32 v106, v106
	v_exp_f32_e32 v107, v107
	v_add_f32_e32 v182, v104, v182
	v_add_f32_e32 v182, v105, v182
	v_cvt_pk_bf16_f32 v140, v104, v105
	s_waitcnt lgkmcnt(6)
	v_mfma_f32_32x32x16_bf16 v[16:31], v[136:139], v[152:155], v[16:31]
	ds_read_b64_tr_b16 v[152:153], v184 offset:13312
	ds_read_b64_tr_b16 v[154:155], v184 offset:15360
	v_exp_f32_e32 v108, v108
	v_exp_f32_e32 v109, v109
	v_add_f32_e32 v182, v106, v182
	v_add_f32_e32 v182, v107, v182
	v_cvt_pk_bf16_f32 v141, v106, v107
	s_waitcnt lgkmcnt(6)
	v_mfma_f32_32x32x16_bf16 v[0:15], v[136:139], v[156:159], v[0:15]
	ds_read_b64_tr_b16 v[156:157], v184 offset:13824
	ds_read_b64_tr_b16 v[158:159], v184 offset:15872
	v_exp_f32_e32 v110, v110
	v_exp_f32_e32 v111, v111
	v_add_f32_e32 v182, v108, v182
	v_add_f32_e32 v182, v109, v182
	v_cvt_pk_bf16_f32 v142, v108, v109
	v_add_f32_e32 v182, v110, v182
	v_add_f32_e32 v182, v111, v182
	v_cvt_pk_bf16_f32 v143, v110, v111
	s_nop 1
	s_waitcnt lgkmcnt(6)
	v_mfma_f32_32x32x16_bf16 v[48:63], v[140:143], v[144:147], v[48:63]
	s_waitcnt lgkmcnt(4)
	v_mfma_f32_32x32x16_bf16 v[32:47], v[140:143], v[148:151], v[32:47]
	s_waitcnt lgkmcnt(2)
	v_mfma_f32_32x32x16_bf16 v[16:31], v[140:143], v[152:155], v[16:31]
	s_waitcnt lgkmcnt(0)
	v_mfma_f32_32x32x16_bf16 v[0:15], v[140:143], v[156:159], v[0:15]
	s_add_i32 s54, s54, 1
	s_add_i32 s55, s55, 0x4000
	s_and_b32 s55, s55, 0xc000
	s_branch .Lsym_done

; template <int KS> __device__ __forceinline__ void pv_ks(f32x16* o, int vb, bf16x8 pa) {
;     const s16x4 l0 = tr_read<v_rd_off(0, KS, 0)>(vb), h0 = tr_read<v_rd_off(0, KS, 1)>(vb), l1 = tr_read<v_rd_off(1, KS, 0)>(vb), h1 = tr_read<v_rd_off(1, KS, 1)>(vb);
;     const s16x4 l2 = tr_read<v_rd_off(2, KS, 0)>(vb), h2 = tr_read<v_rd_off(2, KS, 1)>(vb), l3 = tr_read<v_rd_off(3, KS, 0)>(vb), h3 = tr_read<v_rd_off(3, KS, 1)>(vb);
;     ...
;     asm volatile("s_waitcnt lgkmcnt(6)" ::: "memory"); SBAR();
;     o[0] = __builtin_amdgcn_mfma_f32_32x32x16_bf16(pa, PK(l0, h0), o[0], 0, 0, 0);
;     asm volatile("s_waitcnt lgkmcnt(4)" ::: "memory"); SBAR();
;     o[1] = __builtin_amdgcn_mfma_f32_32x32x16_bf16(pa, PK(l1, h1), o[1], 0, 0, 0);
;     asm volatile("s_waitcnt lgkmcnt(2)" ::: "memory"); SBAR();
;     o[2] = __builtin_amdgcn_mfma_f32_32x32x16_bf16(pa, PK(l2, h2), o[2], 0, 0, 0);
;     asm volatile("s_waitcnt lgkmcnt(0)" ::: "memory"); SBAR();
;     o[3] = __builtin_amdgcn_mfma_f32_32x32x16_bf16(pa, PK(l3, h3), o[3], 0, 0, 0);
;     ...
; }
; __device__ __forceinline__ void pv_d0(f32x16* o, int vb, bf16x8 pa0, bf16x8 pa1, bf16x8 pa2, bf16x8 pa3) {
;     __builtin_amdgcn_s_setprio(1);
;     pv_ks<0>(o, vb, pa0); pv_ks<1>(o, vb, pa1); pv_ks<2>(o, vb, pa2); pv_ks<3>(o, vb, pa3);
;     __builtin_amdgcn_s_setprio(0);
; }
; __device__ __forceinline__ void exp_half(f32x16& p) {
; #pragma unroll
;     for (int r = 0; r < 16; ++r) p[r] = __builtin_amdgcn_exp2f(p[r]);
; }
; __device__ __forceinline__ void pack_p(const f32x16& p0, const f32x16& p1, float& l_reg, bf16x8& pa0, bf16x8& pa1, bf16x8& pa2, bf16x8& pa3) {
; __device__ __forceinline__ void diff_unit(const DiffArgs& A, int b, int h, int qb, char* lds, int wv) {
;     ...
;         for (int j = 1; j + 1 < NT; j += 2) {
;             STAGE(j + 1);
;             SBAR(); BIAS(pB0, pB1, j); qkt<4>(pB0, pB1, K_lds + SLOT(j), qr, r32p, hip, colB0);
;             exp_half(pA1); pack_p(pA0, pA1, l_reg, pa0, pa1, pa2, pa3); SBAR();
;             pv_d0(o, vb0 + SLOT(j - 1), pa0, pa1, pa2, pa3); exp_half(pB0);
;             ENDI();
;             STAGE(j + 2);
;             SBAR(); BIAS(pA0, pA1, j + 1); qkt<4>(pA0, pA1, K_lds + SLOT(j + 1), qr, r32p, hip, colB0);
;             exp_half(pB1); pack_p(pB0, pB1, l_reg, pa0, pa1, pa2, pa3); SBAR();
;             pv_d0(o, vb0 + SLOT(j), pa0, pa1, pa2, pa3); exp_half(pA0);
;             ENDI();
;         }
.Lsym_biasdone_entB:
.Lsym_loopB:
	s_waitcnt vmcnt(0)
	s_barrier
	s_add_i32 s53, s55, 0x4000
	s_and_b32 s53, s53, 0xc000
	s_add_i32 s53, s53, 0x10000
	v_add_u32_e32 v196, s53, v178
	ds_read_b128 v[192:195], v196
	ds_read_b128 v[196:199], v196 offset:8192
	v_add_u32_e32 v204, s53, v179
	ds_read_b128 v[200:203], v204
	ds_read_b128 v[204:207], v204 offset:8192
	v_add_u32_e32 v212, s53, v180
	ds_read_b128 v[208:211], v212
	ds_read_b128 v[212:215], v212 offset:8192
	v_add_u32_e32 v220, s53, v181
	ds_read_b128 v[216:219], v220
	ds_read_b128 v[220:223], v220 offset:8192
	s_add_i32 s53, s54, 2
	s_cmp_le_i32 s53, s62
	s_cbranch_scc0 .Lsym_nostage_eB
	s_add_i32 s53, s25, s58
	s_mov_b32 m0, s53
	s_add_u32 s60, s56, 0x70000
	s_addc_u32 s61, s57, 0
	global_load_lds_dwordx4 v176, s[56:57]
	s_add_i32 m0, s53, 0x2000
	s_nop 0
	global_load_lds_dwordx4 v176, s[60:61]
	s_add_i32 s53, s24, s58
	s_mov_b32 m0, s53
	s_nop 0
	global_load_lds_dwordx4 v188, s[56:57]
	s_add_i32 m0, s53, 0x2000
	s_nop 0
	global_load_lds_dwordx4 v188, s[60:61]
	s_add_u32 s56, s56, 0xe0000
	s_addc_u32 s57, s57, 0
	s_add_i32 s58, s58, 0x4000
	s_and_b32 s58, s58, 0xc000
.Lsym_nostage_eB:
	v_add_u32_e32 v184, s55, v252
	ds_read_b64_tr_b16 v[144:145], v184 offset:0
	ds_read_b64_tr_b16 v[146:147], v184 offset:2048
	ds_read_b64_tr_b16 v[148:149], v184 offset:512
	ds_read_b64_tr_b16 v[150:151], v184 offset:2560
	ds_read_b64_tr_b16 v[152:153], v184 offset:1024
	ds_read_b64_tr_b16 v[154:155], v184 offset:3072
	ds_read_b64_tr_b16 v[156:157], v184 offset:1536
	ds_read_b64_tr_b16 v[158:159], v184 offset:3584
	s_waitcnt lgkmcnt(6)
	v_mfma_f32_32x32x16_bf16 v[48:63], v[128:131], v[144:147], v[48:63]
	ds_read_b64_tr_b16 v[144:145], v184 offset:4096
	ds_read_b64_tr_b16 v[146:147], v184 offset:6144
	v_exp_f32_e32 v88, v88
	v_exp_f32_e32 v89, v89
	s_waitcnt lgkmcnt(6)
	v_mfma_f32_32x32x16_bf16 v[32:47], v[128:131], v[148:151], v[32:47]
	ds_read_b64_tr_b16 v[148:149], v184 offset:4608
	ds_read_b64_tr_b16 v[150:151], v184 offset:6656
	v_exp_f32_e32 v90, v90
	v_exp_f32_e32 v91, v91
	v_add_f32_e32 v182, v88, v182
	v_add_f32_e32 v182, v89, v182
	v_cvt_pk_bf16_f32 v132, v88, v89
	s_waitcnt lgkmcnt(6)
	v_mfma_f32_32x32x16_bf16 v[16:31], v[128:131], v[152:155], v[16:31]
	ds_read_b64_tr_b16 v[152:153], v184 offset:5120
	ds_read_b64_tr_b16 v[154:155], v184 offset:7168
	v_exp_f32_e32 v92, v92
	v_exp_f32_e32 v93, v93
	v_add_f32_e32 v182, v90, v182
	v_add_f32_e32 v182, v91, v182
	v_cvt_pk_bf16_f32 v133, v90, v91
	s_waitcnt lgkmcnt(6)
	v_mfma_f32_32x32x16_bf16 v[0:15], v[128:131], v[156:159], v[0:15]
	ds_read_b64_tr_b16 v[156:157], v184 offset:5632
	ds_read_b64_tr_b16 v[158:159], v184 offset:7680
	v_exp_f32_e32 v94, v94
	v_exp_f32_e32 v95, v95
	v_add_f32_e32 v182, v92, v182
	v_add_f32_e32 v182, v93, v182
	v_cvt_pk_bf16_f32 v134, v92, v93
	v_add_f32_e32 v182, v94, v182
	v_add_f32_e32 v182, v95, v182
	v_cvt_pk_bf16_f32 v135, v94, v95
	v_mfma_f32_32x32x16_bf16 v[112:127], v[192:195], v[172:175], v[112:127]
	v_mfma_f32_32x32x16_bf16 v[96:111], v[196:199], v[172:175], v[96:111]
	v_mfma_f32_32x32x16_bf16 v[112:127], v[200:203], v[168:171], v[112:127]
	v_mfma_f32_32x32x16_bf16 v[96:111], v[204:207], v[168:171], v[96:111]
	s_waitcnt lgkmcnt(6)
	v_mfma_f32_32x32x16_bf16 v[48:63], v[132:135], v[144:147], v[48:63]
	ds_read_b64_tr_b16 v[144:145], v184 offset:8192
	ds_read_b64_tr_b16 v[146:147], v184 offset:10240
	v_exp_f32_e32 v64, v64
	v_exp_f32_e32 v65, v65
	s_waitcnt lgkmcnt(6)
	v_mfma_f32_32x32x16_bf16 v[32:47], v[132:135], v[148:151], v[32:47]
	ds_read_b64_tr_b16 v[148:149], v184 offset:8704
	ds_read_b64_tr_b16 v[150:151], v184 offset:10752
	v_exp_f32_e32 v66, v66
	v_exp_f32_e32 v67, v67
	v_add_f32_e32 v182, v64, v182
	v_add_f32_e32 v182, v65, v182
	v_cvt_pk_bf16_f32 v136, v64, v65
	s_waitcnt lgkmcnt(6)
	v_mfma_f32_32x32x16_bf16 v[16:31], v[132:135], v[152:155], v[16:31]
	ds_read_b64_tr_b16 v[152:153], v184 offset:9216
	ds_read_b64_tr_b16 v[154:155], v184 offset:11264
	v_exp_f32_e32 v68, v68
	v_exp_f32_e32 v69, v69
	v_add_f32_e32 v182, v66, v182
	v_add_f32_e32 v182, v67, v182
	v_cvt_pk_bf16_f32 v137, v66, v67
	s_waitcnt lgkmcnt(6)
; template <int KS> __device__ __forceinline__ void pv_ks(f32x16* o, int vb, bf16x8 pa) {
;     const s16x4 l0 = tr_read<v_rd_off(0, KS, 0)>(vb), h0 = tr_read<v_rd_off(0, KS, 1)>(vb), l1 = tr_read<v_rd_off(1, KS, 0)>(vb), h1 = tr_read<v_rd_off(1, KS, 1)>(vb);
;     const s16x4 l2 = tr_read<v_rd_off(2, KS, 0)>(vb), h2 = tr_read<v_rd_off(2, KS, 1)>(vb), l3 = tr_read<v_rd_off(3, KS, 0)>(vb), h3 = tr_read<v_rd_off(3, KS, 1)>(vb);
;     ...
;     asm volatile("s_waitcnt lgkmcnt(6)" ::: "memory"); SBAR();
;     o[0] = __builtin_amdgcn_mfma_f32_32x32x16_bf16(pa, PK(l0, h0), o[0], 0, 0, 0);
;     asm volatile("s_waitcnt lgkmcnt(4)" ::: "memory"); SBAR();
;     o[1] = __builtin_amdgcn_mfma_f32_32x32x16_bf16(pa, PK(l1, h1), o[1], 0, 0, 0);
;     asm volatile("s_waitcnt lgkmcnt(2)" ::: "memory"); SBAR();
;     o[2] = __builtin_amdgcn_mfma_f32_32x32x16_bf16(pa, PK(l2, h2), o[2], 0, 0, 0);
;     asm volatile("s_waitcnt lgkmcnt(0)" ::: "memory"); SBAR();
;     o[3] = __builtin_amdgcn_mfma_f32_32x32x16_bf16(pa, PK(l3, h3), o[3], 0, 0, 0);
;     ...
; }
; __device__ __forceinline__ void pv_d0(f32x16* o, int vb, bf16x8 pa0, bf16x8 pa1, bf16x8 pa2, bf16x8 pa3) {
;     __builtin_amdgcn_s_setprio(1);
;     pv_ks<0>(o, vb, pa0); pv_ks<1>(o, vb, pa1); pv_ks<2>(o, vb, pa2); pv_ks<3>(o, vb, pa3);
;     __builtin_amdgcn_s_setprio(0);
; }
; __device__ __forceinline__ void exp_half(f32x16& p) {
; #pragma unroll
;     for (int r = 0; r < 16; ++r) p[r] = __builtin_amdgcn_exp2f(p[r]);
; }
; __device__ __forceinline__ void pack_p(const f32x16& p0, const f32x16& p1, float& l_reg, bf16x8& pa0, bf16x8& pa1, bf16x8& pa2, bf16x8& pa3) {
;     float ps = 0;
; #pragma unroll
;     for (int r = 0; r < 16; ++r) ps += p0[r];
; #pragma unroll
;     for (int r = 0; r < 16; ++r) ps += p1[r];
;     l_reg += ps;
;     ...
;     PK4(p0, 0, pa0); PK4(p0, 8, pa1); PK4(p1, 0, pa2); PK4(p1, 8, pa3);
;     ...
; }
; template <int ND0> __device__ __forceinline__ void qkt(f32x16& p0, f32x16& p1, const char* Ks, const bf16x8* qr, int r32, int hi, int colB0) {
; #pragma unroll
;     for (int d0 = 0; d0 < ND0; ++d0) { const int cb = colB0 + (d0 * 16 + hi * 8) * 2;
;         const bf16x8 b0 = *reinterpret_cast<const bf16x8*>(Ks + KSWZ(r32, cb));
;         const bf16x8 b1 = *reinterpret_cast<const bf16x8*>(Ks + KSWZ(32 + r32, cb));
;         p0 = __builtin_amdgcn_mfma_f32_32x32x16_bf16(b0, qr[d0], p0, 0, 0, 0);
	v_mfma_f32_32x32x16_bf16 v[0:15], v[132:135], v[156:159], v[0:15]
	ds_read_b64_tr_b16 v[156:157], v184 offset:9728
	ds_read_b64_tr_b16 v[158:159], v184 offset:11776
	v_exp_f32_e32 v70, v70
	v_exp_f32_e32 v71, v71
	v_add_f32_e32 v182, v68, v182
	v_add_f32_e32 v182, v69, v182
	v_cvt_pk_bf16_f32 v138, v68, v69
	v_add_f32_e32 v182, v70, v182
	v_add_f32_e32 v182, v71, v182
	v_cvt_pk_bf16_f32 v139, v70, v71
	v_mfma_f32_32x32x16_bf16 v[112:127], v[208:211], v[164:167], v[112:127]
	v_mfma_f32_32x32x16_bf16 v[96:111], v[212:215], v[164:167], v[96:111]
	v_mfma_f32_32x32x16_bf16 v[112:127], v[216:219], v[160:163], v[112:127]
	v_mfma_f32_32x32x16_bf16 v[96:111], v[220:223], v[160:163], v[96:111]
	s_waitcnt lgkmcnt(6)
	v_mfma_f32_32x32x16_bf16 v[48:63], v[136:139], v[144:147], v[48:63]
	ds_read_b64_tr_b16 v[144:145], v184 offset:12288
	ds_read_b64_tr_b16 v[146:147], v184 offset:14336
	v_exp_f32_e32 v72, v72
	v_exp_f32_e32 v73, v73
	s_waitcnt lgkmcnt(6)
	v_mfma_f32_32x32x16_bf16 v[32:47], v[136:139], v[148:151], v[32:47]
	ds_read_b64_tr_b16 v[148:149], v184 offset:12800
	ds_read_b64_tr_b16 v[150:151], v184 offset:14848
	v_exp_f32_e32 v74, v74
	v_exp_f32_e32 v75, v75
	v_add_f32_e32 v182, v72, v182
	v_add_f32_e32 v182, v73, v182
	v_cvt_pk_bf16_f32 v140, v72, v73
	s_waitcnt lgkmcnt(6)
	v_mfma_f32_32x32x16_bf16 v[16:31], v[136:139], v[152:155], v[16:31]
	ds_read_b64_tr_b16 v[152:153], v184 offset:13312
	ds_read_b64_tr_b16 v[154:155], v184 offset:15360
	v_exp_f32_e32 v76, v76
	v_exp_f32_e32 v77, v77
	v_add_f32_e32 v182, v74, v182
	v_add_f32_e32 v182, v75, v182
	v_cvt_pk_bf16_f32 v141, v74, v75
	s_waitcnt lgkmcnt(6)
	v_mfma_f32_32x32x16_bf16 v[0:15], v[136:139], v[156:159], v[0:15]
	ds_read_b64_tr_b16 v[156:157], v184 offset:13824
	ds_read_b64_tr_b16 v[158:159], v184 offset:15872
	v_exp_f32_e32 v78, v78
	v_exp_f32_e32 v79, v79
	v_add_f32_e32 v182, v76, v182
	v_add_f32_e32 v182, v77, v182
	v_cvt_pk_bf16_f32 v142, v76, v77
	v_add_f32_e32 v182, v78, v182
	v_add_f32_e32 v182, v79, v182
	v_cvt_pk_bf16_f32 v143, v78, v79
	s_nop 1
	s_waitcnt lgkmcnt(6)
	v_mfma_f32_32x32x16_bf16 v[48:63], v[140:143], v[144:147], v[48:63]
	v_exp_f32_e32 v112, v112
	v_exp_f32_e32 v113, v113
	s_waitcnt lgkmcnt(4)
	v_mfma_f32_32x32x16_bf16 v[32:47], v[140:143], v[148:151], v[32:47]
	v_exp_f32_e32 v114, v114
	v_exp_f32_e32 v115, v115
	v_add_f32_e32 v182, v112, v182
	v_add_f32_e32 v182, v113, v182
	v_cvt_pk_bf16_f32 v128, v112, v113
	s_waitcnt lgkmcnt(2)
	v_mfma_f32_32x32x16_bf16 v[16:31], v[140:143], v[152:155], v[16:31]
	v_exp_f32_e32 v116, v116
	v_exp_f32_e32 v117, v117
	v_add_f32_e32 v182, v114, v182
	v_add_f32_e32 v182, v115, v182
	v_cvt_pk_bf16_f32 v129, v114, v115
	s_waitcnt lgkmcnt(0)
	v_mfma_f32_32x32x16_bf16 v[0:15], v[140:143], v[156:159], v[0:15]
	v_exp_f32_e32 v118, v118
	v_exp_f32_e32 v119, v119
	v_add_f32_e32 v182, v116, v182
	v_add_f32_e32 v182, v117, v182
	v_cvt_pk_bf16_f32 v130, v116, v117
	v_add_f32_e32 v182, v118, v182
	v_add_f32_e32 v182, v119, v182
	v_cvt_pk_bf16_f32 v131, v118, v119
	s_nop 1
	s_add_i32 s53, s54, 2
	s_cmp_le_i32 s53, s62
	s_cbranch_scc0 .Lsym_biasdone_eB
	s_lshl_b32 s53, s53, 6
	v_subrev_u32_e32 v183, s53, v236
	v_cvt_f32_i32_e32 v183, v183
	s_add_i32 s53, s53, s63
	s_add_i32 s100, s53, 62
	s_cmp_lt_u32 s100, 93
	s_cbranch_scc1 .Lsym_diag_eB
	s_cmp_lt_i32 s53, 0
	s_cselect_b32 s100, -1.0, 1.0
	v_mul_f32_e32 v185, s100, v186
	v_fma_f32 v187, -v185, v183, s16
	v_fmamk_f32 v80, v185, 0x00000000, v187
	v_fmamk_f32 v64, v185, 0x42000000, v187
	v_fmamk_f32 v81, v185, 0x3f800000, v187
	v_fmamk_f32 v65, v185, 0x42040000, v187
	v_fmamk_f32 v82, v185, 0x40000000, v187
	v_fmamk_f32 v66, v185, 0x42080000, v187
	v_fmamk_f32 v83, v185, 0x40400000, v187
	v_fmamk_f32 v67, v185, 0x420c0000, v187
	v_fmamk_f32 v84, v185, 0x41000000, v187
	v_fmamk_f32 v68, v185, 0x42200000, v187
	v_fmamk_f32 v85, v185, 0x41100000, v187
	v_fmamk_f32 v69, v185, 0x42240000, v187
	v_fmamk_f32 v86, v185, 0x41200000, v187
	v_fmamk_f32 v70, v185, 0x42280000, v187
	v_fmamk_f32 v87, v185, 0x41300000, v187
	v_fmamk_f32 v71, v185, 0x422c0000, v187
	v_fmamk_f32 v88, v185, 0x41800000, v187
	v_fmamk_f32 v72, v185, 0x42400000, v187
	v_fmamk_f32 v89, v185, 0x41880000, v187
	v_fmamk_f32 v73, v185, 0x42440000, v187
	v_fmamk_f32 v90, v185, 0x41900000, v187
	v_fmamk_f32 v74, v185, 0x42480000, v187
	v_fmamk_f32 v91, v185, 0x41980000, v187
	v_fmamk_f32 v75, v185, 0x424c0000, v187
	v_fmamk_f32 v92, v185, 0x41c00000, v187
	v_fmamk_f32 v76, v185, 0x42600000, v187
	v_fmamk_f32 v93, v185, 0x41c80000, v187
	v_fmamk_f32 v77, v185, 0x42640000, v187
	v_fmamk_f32 v94, v185, 0x41d00000, v187
	v_fmamk_f32 v78, v185, 0x42680000, v187
	v_fmamk_f32 v95, v185, 0x41d80000, v187
	v_fmamk_f32 v79, v185, 0x426c0000, v187
	s_branch .Lsym_biasdone_eB

; template <int KS> __device__ __forceinline__ void pv_ks(f32x16* o, int vb, bf16x8 pa) {
;     const s16x4 l0 = tr_read<v_rd_off(0, KS, 0)>(vb), h0 = tr_read<v_rd_off(0, KS, 1)>(vb), l1 = tr_read<v_rd_off(1, KS, 0)>(vb), h1 = tr_read<v_rd_off(1, KS, 1)>(vb);
;     const s16x4 l2 = tr_read<v_rd_off(2, KS, 0)>(vb), h2 = tr_read<v_rd_off(2, KS, 1)>(vb), l3 = tr_read<v_rd_off(3, KS, 0)>(vb), h3 = tr_read<v_rd_off(3, KS, 1)>(vb);
;     ...
;     asm volatile("s_waitcnt lgkmcnt(6)" ::: "memory"); SBAR();
;     o[0] = __builtin_amdgcn_mfma_f32_32x32x16_bf16(pa, PK(l0, h0), o[0], 0, 0, 0);
;     asm volatile("s_waitcnt lgkmcnt(4)" ::: "memory"); SBAR();
;     o[1] = __builtin_amdgcn_mfma_f32_32x32x16_bf16(pa, PK(l1, h1), o[1], 0, 0, 0);
;     asm volatile("s_waitcnt lgkmcnt(2)" ::: "memory"); SBAR();
;     o[2] = __builtin_amdgcn_mfma_f32_32x32x16_bf16(pa, PK(l2, h2), o[2], 0, 0, 0);
;     asm volatile("s_waitcnt lgkmcnt(0)" ::: "memory"); SBAR();
;     o[3] = __builtin_amdgcn_mfma_f32_32x32x16_bf16(pa, PK(l3, h3), o[3], 0, 0, 0);
;     ...
; }
; __device__ __forceinline__ void pv_d0(f32x16* o, int vb, bf16x8 pa0, bf16x8 pa1, bf16x8 pa2, bf16x8 pa3) {
;     __builtin_amdgcn_s_setprio(1);
;     pv_ks<0>(o, vb, pa0); pv_ks<1>(o, vb, pa1); pv_ks<2>(o, vb, pa2); pv_ks<3>(o, vb, pa3);
;     __builtin_amdgcn_s_setprio(0);
; }
; __device__ __forceinline__ void exp_half(f32x16& p) {
; #pragma unroll
;     for (int r = 0; r < 16; ++r) p[r] = __builtin_amdgcn_exp2f(p[r]);
; }
; __device__ __forceinline__ void pack_p(const f32x16& p0, const f32x16& p1, float& l_reg, bf16x8& pa0, bf16x8& pa1, bf16x8& pa2, bf16x8& pa3) {
; __device__ __forceinline__ void diff_unit(const DiffArgs& A, int b, int h, int qb, char* lds, int wv) {
;     ...
;         for (int j = 1; j + 1 < NT; j += 2) {
;             STAGE(j + 1);
;             SBAR(); BIAS(pB0, pB1, j); qkt<4>(pB0, pB1, K_lds + SLOT(j), qr, r32p, hip, colB0);
;             exp_half(pA1); pack_p(pA0, pA1, l_reg, pa0, pa1, pa2, pa3); SBAR();
;             pv_d0(o, vb0 + SLOT(j - 1), pa0, pa1, pa2, pa3); exp_half(pB0);
;             ENDI();
;             STAGE(j + 2);
;             SBAR(); BIAS(pA0, pA1, j + 1); qkt<4>(pA0, pA1, K_lds + SLOT(j + 1), qr, r32p, hip, colB0);
;             exp_half(pB1); pack_p(pB0, pB1, l_reg, pa0, pa1, pa2, pa3); SBAR();
;             pv_d0(o, vb0 + SLOT(j), pa0, pa1, pa2, pa3); exp_half(pA0);
;             ENDI();
;         }
.Lsym_biasdone_eB:
	s_add_i32 s54, s54, 1
	s_add_i32 s55, s55, 0x4000
	s_and_b32 s55, s55, 0xc000
	s_cmp_ge_i32 s54, s62
	s_cbranch_scc1 .Lsym_lastB
	s_waitcnt vmcnt(0)
	s_barrier
	s_add_i32 s53, s55, 0x4000
	s_and_b32 s53, s53, 0xc000
	s_add_i32 s53, s53, 0x10000
	v_add_u32_e32 v196, s53, v178
	ds_read_b128 v[192:195], v196
	ds_read_b128 v[196:199], v196 offset:8192
	v_add_u32_e32 v204, s53, v179
	ds_read_b128 v[200:203], v204
	ds_read_b128 v[204:207], v204 offset:8192
	v_add_u32_e32 v212, s53, v180
	ds_read_b128 v[208:211], v212
	ds_read_b128 v[212:215], v212 offset:8192
	v_add_u32_e32 v220, s53, v181
	ds_read_b128 v[216:219], v220
	ds_read_b128 v[220:223], v220 offset:8192
	s_add_i32 s53, s54, 2
	s_cmp_le_i32 s53, s62
	s_cbranch_scc0 .Lsym_nostage_oB
	s_add_i32 s53, s25, s58
	s_mov_b32 m0, s53
	s_add_u32 s60, s56, 0x70000
	s_addc_u32 s61, s57, 0
	global_load_lds_dwordx4 v176, s[56:57]
	s_add_i32 m0, s53, 0x2000
	s_nop 0
	global_load_lds_dwordx4 v176, s[60:61]
	s_add_i32 s53, s24, s58
	s_mov_b32 m0, s53
	s_nop 0
	global_load_lds_dwordx4 v188, s[56:57]
	s_add_i32 m0, s53, 0x2000
	s_nop 0
	global_load_lds_dwordx4 v188, s[60:61]
	s_add_u32 s56, s56, 0xe0000
	s_addc_u32 s57, s57, 0
	s_add_i32 s58, s58, 0x4000
	s_and_b32 s58, s58, 0xc000
.Lsym_nostage_oB:
	v_add_u32_e32 v184, s55, v252
	ds_read_b64_tr_b16 v[144:145], v184 offset:0
	ds_read_b64_tr_b16 v[146:147], v184 offset:2048
	ds_read_b64_tr_b16 v[148:149], v184 offset:512
	ds_read_b64_tr_b16 v[150:151], v184 offset:2560
	ds_read_b64_tr_b16 v[152:153], v184 offset:1024
	ds_read_b64_tr_b16 v[154:155], v184 offset:3072
	ds_read_b64_tr_b16 v[156:157], v184 offset:1536
	ds_read_b64_tr_b16 v[158:159], v184 offset:3584
	s_waitcnt lgkmcnt(6)
	v_mfma_f32_32x32x16_bf16 v[48:63], v[128:131], v[144:147], v[48:63]
	ds_read_b64_tr_b16 v[144:145], v184 offset:4096
	ds_read_b64_tr_b16 v[146:147], v184 offset:6144
	v_exp_f32_e32 v120, v120
	v_exp_f32_e32 v121, v121
	s_waitcnt lgkmcnt(6)
	v_mfma_f32_32x32x16_bf16 v[32:47], v[128:131], v[148:151], v[32:47]
	ds_read_b64_tr_b16 v[148:149], v184 offset:4608
	ds_read_b64_tr_b16 v[150:151], v184 offset:6656
	v_exp_f32_e32 v122, v122
	v_exp_f32_e32 v123, v123
	v_add_f32_e32 v182, v120, v182
	v_add_f32_e32 v182, v121, v182
	v_cvt_pk_bf16_f32 v132, v120, v121
	s_waitcnt lgkmcnt(6)
	v_mfma_f32_32x32x16_bf16 v[16:31], v[128:131], v[152:155], v[16:31]
	ds_read_b64_tr_b16 v[152:153], v184 offset:5120
	ds_read_b64_tr_b16 v[154:155], v184 offset:7168
	v_exp_f32_e32 v124, v124
	v_exp_f32_e32 v125, v125
	v_add_f32_e32 v182, v122, v182
	v_add_f32_e32 v182, v123, v182
	v_cvt_pk_bf16_f32 v133, v122, v123
	s_waitcnt lgkmcnt(6)
	v_mfma_f32_32x32x16_bf16 v[0:15], v[128:131], v[156:159], v[0:15]
	ds_read_b64_tr_b16 v[156:157], v184 offset:5632
	ds_read_b64_tr_b16 v[158:159], v184 offset:7680
	v_exp_f32_e32 v126, v126
	v_exp_f32_e32 v127, v127
	v_add_f32_e32 v182, v124, v182
	v_add_f32_e32 v182, v125, v182
	v_cvt_pk_bf16_f32 v134, v124, v125
	v_add_f32_e32 v182, v126, v182
	v_add_f32_e32 v182, v127, v182
	v_cvt_pk_bf16_f32 v135, v126, v127
	v_mfma_f32_32x32x16_bf16 v[80:95], v[192:195], v[172:175], v[80:95]
	v_mfma_f32_32x32x16_bf16 v[64:79], v[196:199], v[172:175], v[64:79]
	v_mfma_f32_32x32x16_bf16 v[80:95], v[200:203], v[168:171], v[80:95]
	v_mfma_f32_32x32x16_bf16 v[64:79], v[204:207], v[168:171], v[64:79]
	s_waitcnt lgkmcnt(6)
	v_mfma_f32_32x32x16_bf16 v[48:63], v[132:135], v[144:147], v[48:63]
	ds_read_b64_tr_b16 v[144:145], v184 offset:8192
	ds_read_b64_tr_b16 v[146:147], v184 offset:10240
	v_exp_f32_e32 v96, v96
	v_exp_f32_e32 v97, v97
	s_waitcnt lgkmcnt(6)
	v_mfma_f32_32x32x16_bf16 v[32:47], v[132:135], v[148:151], v[32:47]
	ds_read_b64_tr_b16 v[148:149], v184 offset:8704
	ds_read_b64_tr_b16 v[150:151], v184 offset:10752
	v_exp_f32_e32 v98, v98
	v_exp_f32_e32 v99, v99
	v_add_f32_e32 v182, v96, v182
	v_add_f32_e32 v182, v97, v182
	v_cvt_pk_bf16_f32 v136, v96, v97
	s_waitcnt lgkmcnt(6)
	v_mfma_f32_32x32x16_bf16 v[16:31], v[132:135], v[152:155], v[16:31]
	ds_read_b64_tr_b16 v[152:153], v184 offset:9216
	ds_read_b64_tr_b16 v[154:155], v184 offset:11264
	v_exp_f32_e32 v100, v100
	v_exp_f32_e32 v101, v101
	v_add_f32_e32 v182, v98, v182
	v_add_f32_e32 v182, v99, v182
	v_cvt_pk_bf16_f32 v137, v98, v99
	s_waitcnt lgkmcnt(6)
; template <int KS> __device__ __forceinline__ void pv_ks(f32x16* o, int vb, bf16x8 pa) {
;     const s16x4 l0 = tr_read<v_rd_off(0, KS, 0)>(vb), h0 = tr_read<v_rd_off(0, KS, 1)>(vb), l1 = tr_read<v_rd_off(1, KS, 0)>(vb), h1 = tr_read<v_rd_off(1, KS, 1)>(vb);
;     const s16x4 l2 = tr_read<v_rd_off(2, KS, 0)>(vb), h2 = tr_read<v_rd_off(2, KS, 1)>(vb), l3 = tr_read<v_rd_off(3, KS, 0)>(vb), h3 = tr_read<v_rd_off(3, KS, 1)>(vb);
;     ...
;     asm volatile("s_waitcnt lgkmcnt(6)" ::: "memory"); SBAR();
;     o[0] = __builtin_amdgcn_mfma_f32_32x32x16_bf16(pa, PK(l0, h0), o[0], 0, 0, 0);
;     asm volatile("s_waitcnt lgkmcnt(4)" ::: "memory"); SBAR();
;     o[1] = __builtin_amdgcn_mfma_f32_32x32x16_bf16(pa, PK(l1, h1), o[1], 0, 0, 0);
;     asm volatile("s_waitcnt lgkmcnt(2)" ::: "memory"); SBAR();
;     o[2] = __builtin_amdgcn_mfma_f32_32x32x16_bf16(pa, PK(l2, h2), o[2], 0, 0, 0);
;     asm volatile("s_waitcnt lgkmcnt(0)" ::: "memory"); SBAR();
;     o[3] = __builtin_amdgcn_mfma_f32_32x32x16_bf16(pa, PK(l3, h3), o[3], 0, 0, 0);
;     ...
; }
; __device__ __forceinline__ void pv_d0(f32x16* o, int vb, bf16x8 pa0, bf16x8 pa1, bf16x8 pa2, bf16x8 pa3) {
;     __builtin_amdgcn_s_setprio(1);
;     pv_ks<0>(o, vb, pa0); pv_ks<1>(o, vb, pa1); pv_ks<2>(o, vb, pa2); pv_ks<3>(o, vb, pa3);
;     __builtin_amdgcn_s_setprio(0);
; }
; __device__ __forceinline__ void exp_half(f32x16& p) {
; #pragma unroll
;     for (int r = 0; r < 16; ++r) p[r] = __builtin_amdgcn_exp2f(p[r]);
; }
; __device__ __forceinline__ void pack_p(const f32x16& p0, const f32x16& p1, float& l_reg, bf16x8& pa0, bf16x8& pa1, bf16x8& pa2, bf16x8& pa3) {
;     float ps = 0;
; #pragma unroll
;     for (int r = 0; r < 16; ++r) ps += p0[r];
; #pragma unroll
;     for (int r = 0; r < 16; ++r) ps += p1[r];
;     l_reg += ps;
;     ...
;     PK4(p0, 0, pa0); PK4(p0, 8, pa1); PK4(p1, 0, pa2); PK4(p1, 8, pa3);
;     ...
; }
; template <int ND0> __device__ __forceinline__ void qkt(f32x16& p0, f32x16& p1, const char* Ks, const bf16x8* qr, int r32, int hi, int colB0) {
; #pragma unroll
;     for (int d0 = 0; d0 < ND0; ++d0) { const int cb = colB0 + (d0 * 16 + hi * 8) * 2;
;         const bf16x8 b0 = *reinterpret_cast<const bf16x8*>(Ks + KSWZ(r32, cb));
;         const bf16x8 b1 = *reinterpret_cast<const bf16x8*>(Ks + KSWZ(32 + r32, cb));
;         p0 = __builtin_amdgcn_mfma_f32_32x32x16_bf16(b0, qr[d0], p0, 0, 0, 0);
	v_mfma_f32_32x32x16_bf16 v[0:15], v[132:135], v[156:159], v[0:15]
	ds_read_b64_tr_b16 v[156:157], v184 offset:9728
	ds_read_b64_tr_b16 v[158:159], v184 offset:11776
	v_exp_f32_e32 v102, v102
	v_exp_f32_e32 v103, v103
	v_add_f32_e32 v182, v100, v182
	v_add_f32_e32 v182, v101, v182
	v_cvt_pk_bf16_f32 v138, v100, v101
	v_add_f32_e32 v182, v102, v182
	v_add_f32_e32 v182, v103, v182
	v_cvt_pk_bf16_f32 v139, v102, v103
	v_mfma_f32_32x32x16_bf16 v[80:95], v[208:211], v[164:167], v[80:95]
	v_mfma_f32_32x32x16_bf16 v[64:79], v[212:215], v[164:167], v[64:79]
	v_mfma_f32_32x32x16_bf16 v[80:95], v[216:219], v[160:163], v[80:95]
	v_mfma_f32_32x32x16_bf16 v[64:79], v[220:223], v[160:163], v[64:79]
	s_waitcnt lgkmcnt(6)
	v_mfma_f32_32x32x16_bf16 v[48:63], v[136:139], v[144:147], v[48:63]
	ds_read_b64_tr_b16 v[144:145], v184 offset:12288
	ds_read_b64_tr_b16 v[146:147], v184 offset:14336
	v_exp_f32_e32 v104, v104
	v_exp_f32_e32 v105, v105
	s_waitcnt lgkmcnt(6)
	v_mfma_f32_32x32x16_bf16 v[32:47], v[136:139], v[148:151], v[32:47]
	ds_read_b64_tr_b16 v[148:149], v184 offset:12800
	ds_read_b64_tr_b16 v[150:151], v184 offset:14848
	v_exp_f32_e32 v106, v106
	v_exp_f32_e32 v107, v107
	v_add_f32_e32 v182, v104, v182
	v_add_f32_e32 v182, v105, v182
	v_cvt_pk_bf16_f32 v140, v104, v105
	s_waitcnt lgkmcnt(6)
	v_mfma_f32_32x32x16_bf16 v[16:31], v[136:139], v[152:155], v[16:31]
	ds_read_b64_tr_b16 v[152:153], v184 offset:13312
	ds_read_b64_tr_b16 v[154:155], v184 offset:15360
	v_exp_f32_e32 v108, v108
	v_exp_f32_e32 v109, v109
	v_add_f32_e32 v182, v106, v182
	v_add_f32_e32 v182, v107, v182
	v_cvt_pk_bf16_f32 v141, v106, v107
	s_waitcnt lgkmcnt(6)
	v_mfma_f32_32x32x16_bf16 v[0:15], v[136:139], v[156:159], v[0:15]
	ds_read_b64_tr_b16 v[156:157], v184 offset:13824
	ds_read_b64_tr_b16 v[158:159], v184 offset:15872
	v_exp_f32_e32 v110, v110
	v_exp_f32_e32 v111, v111
	v_add_f32_e32 v182, v108, v182
	v_add_f32_e32 v182, v109, v182
	v_cvt_pk_bf16_f32 v142, v108, v109
	v_add_f32_e32 v182, v110, v182
	v_add_f32_e32 v182, v111, v182
	v_cvt_pk_bf16_f32 v143, v110, v111
	s_nop 1
	s_waitcnt lgkmcnt(6)
	v_mfma_f32_32x32x16_bf16 v[48:63], v[140:143], v[144:147], v[48:63]
	v_exp_f32_e32 v80, v80
	v_exp_f32_e32 v81, v81
	s_waitcnt lgkmcnt(4)
	v_mfma_f32_32x32x16_bf16 v[32:47], v[140:143], v[148:151], v[32:47]
	v_exp_f32_e32 v82, v82
	v_exp_f32_e32 v83, v83
	v_add_f32_e32 v182, v80, v182
	v_add_f32_e32 v182, v81, v182
	v_cvt_pk_bf16_f32 v128, v80, v81
	s_waitcnt lgkmcnt(2)
	v_mfma_f32_32x32x16_bf16 v[16:31], v[140:143], v[152:155], v[16:31]
	v_exp_f32_e32 v84, v84
	v_exp_f32_e32 v85, v85
	v_add_f32_e32 v182, v82, v182
	v_add_f32_e32 v182, v83, v182
	v_cvt_pk_bf16_f32 v129, v82, v83
	s_waitcnt lgkmcnt(0)
	v_mfma_f32_32x32x16_bf16 v[0:15], v[140:143], v[156:159], v[0:15]
	v_exp_f32_e32 v86, v86
	v_exp_f32_e32 v87, v87
	v_add_f32_e32 v182, v84, v182
	v_add_f32_e32 v182, v85, v182
	v_cvt_pk_bf16_f32 v130, v84, v85
	v_add_f32_e32 v182, v86, v182
	v_add_f32_e32 v182, v87, v182
	v_cvt_pk_bf16_f32 v131, v86, v87
	s_nop 1
	s_add_i32 s53, s54, 2
	s_cmp_le_i32 s53, s62
	s_cbranch_scc0 .Lsym_biasdone_oB
	s_lshl_b32 s53, s53, 6
	v_subrev_u32_e32 v183, s53, v236
	v_cvt_f32_i32_e32 v183, v183
	s_add_i32 s53, s53, s63
	s_add_i32 s100, s53, 62
	s_cmp_lt_u32 s100, 93
	s_cbranch_scc1 .Lsym_diag_oB
	s_cmp_lt_i32 s53, 0
	s_cselect_b32 s100, -1.0, 1.0
	v_mul_f32_e32 v185, s100, v186
	v_fma_f32 v187, -v185, v183, s16
	v_fmamk_f32 v112, v185, 0x00000000, v187
	v_fmamk_f32 v96, v185, 0x42000000, v187
	v_fmamk_f32 v113, v185, 0x3f800000, v187
	v_fmamk_f32 v97, v185, 0x42040000, v187
	v_fmamk_f32 v114, v185, 0x40000000, v187
	v_fmamk_f32 v98, v185, 0x42080000, v187
	v_fmamk_f32 v115, v185, 0x40400000, v187
	v_fmamk_f32 v99, v185, 0x420c0000, v187
	v_fmamk_f32 v116, v185, 0x41000000, v187
	v_fmamk_f32 v100, v185, 0x42200000, v187
	v_fmamk_f32 v117, v185, 0x41100000, v187
	v_fmamk_f32 v101, v185, 0x42240000, v187
	v_fmamk_f32 v118, v185, 0x41200000, v187
	v_fmamk_f32 v102, v185, 0x42280000, v187
	v_fmamk_f32 v119, v185, 0x41300000, v187
	v_fmamk_f32 v103, v185, 0x422c0000, v187
	v_fmamk_f32 v120, v185, 0x41800000, v187
	v_fmamk_f32 v104, v185, 0x42400000, v187
	v_fmamk_f32 v121, v185, 0x41880000, v187
	v_fmamk_f32 v105, v185, 0x42440000, v187
	v_fmamk_f32 v122, v185, 0x41900000, v187
	v_fmamk_f32 v106, v185, 0x42480000, v187
	v_fmamk_f32 v123, v185, 0x41980000, v187
	v_fmamk_f32 v107, v185, 0x424c0000, v187
	v_fmamk_f32 v124, v185, 0x41c00000, v187
	v_fmamk_f32 v108, v185, 0x42600000, v187
	v_fmamk_f32 v125, v185, 0x41c80000, v187
	v_fmamk_f32 v109, v185, 0x42640000, v187
	v_fmamk_f32 v126, v185, 0x41d00000, v187
	v_fmamk_f32 v110, v185, 0x42680000, v187
	v_fmamk_f32 v127, v185, 0x41d80000, v187
	v_fmamk_f32 v111, v185, 0x426c0000, v187
	s_branch .Lsym_biasdone_oB

; #define SBAR() __builtin_amdgcn_sched_barrier(0)
; #define STAGE(t) do { const char* kt_ = Pk + (size_t)((t) * KVBLK) * (INC * 2); const int so_ = ((t) & 3) * SHM_K; \
;     GLDS(kt_ + koff, ldsA + 4 * SHM_V + so_); GLDS(kt_ + 32 * INC * 2 + koff, ldsA + 4 * SHM_V + so_ + 8192); \
;     GLDS(kt_ + voff, ldsA + so_); GLDS(kt_ + 32 * INC * 2 + voff, ldsA + so_ + 8192); } while (0)
; #define ENDI() do { asm volatile("s_waitcnt vmcnt(0)" ::: "memory"); __syncthreads(); } while (0)
; #define BIAS(P0, P1, t) bias_init(P0, P1, (float)(iposk - (t) * KVBLK), nslope2, nM2, relw + (t) * KVBLK)
; __device__ __forceinline__ void diff_unit(const DiffArgs& A, int b, int h, int qb, char* lds, int wv) {
;     ...
; #pragma unroll 1
;         for (int j = 1; j + 1 < NT; j += 2) {
;             STAGE(j + 1);
;             SBAR(); BIAS(pB0, pB1, j); qkt<4>(pB0, pB1, K_lds + SLOT(j), qr, r32p, hip, colB0);
;             exp_half(pA1); pack_p(pA0, pA1, l_reg, pa0, pa1, pa2, pa3); SBAR();
;             pv_d0(o, vb0 + SLOT(j - 1), pa0, pa1, pa2, pa3); exp_half(pB0);
;             ENDI();
;             STAGE(j + 2);
;             SBAR(); BIAS(pA0, pA1, j + 1); qkt<4>(pA0, pA1, K_lds + SLOT(j + 1), qr, r32p, hip, colB0);
;             exp_half(pB1); pack_p(pB0, pB1, l_reg, pa0, pa1, pa2, pa3); SBAR();
;             pv_d0(o, vb0 + SLOT(j), pa0, pa1, pa2, pa3); exp_half(pA0);
;             ENDI();
;         }
.Lsym_biasdone_oB:
	s_add_i32 s54, s54, 1
	s_add_i32 s55, s55, 0x4000
	s_and_b32 s55, s55, 0xc000
	s_branch .Lsym_loopB

; __device__ __forceinline__ void diff_unit(const DiffArgs& A, int b, int h, int qb, char* lds, int wv) {
;     ...
;     { auto rr = __builtin_amdgcn_permlane32_swap(__float_as_uint(l_reg), __float_as_uint(l_reg), false, false);
;       l_reg = __uint_as_float(rr[0]) + __uint_as_float(rr[1]); }
.Lsym_done:
	v_mov_b32_e32 v96, v182
